# v6: + q/kv row-norm and ssm2 C-fragment load ladders: loads hoisted to the top of the block into free VGPRs (q loop unrolled), counted vmcnt
# speedup vs baseline: 1.0250x; 1.0005x over previous
; DI u32x4 pack8(const float* f) { u32x4 o; o.x = pack2(f[0], f[1]); o.y = pack2(f[2], f[3]); o.z = pack2(f[4], f[5]); o.w = pack2(f[6], f[7]); return o; }
; DI void ssm2_item(PREF p, int l, int item, unsigned char* ldsb) {
;     ...
;   const int hcol = lane & 15, q4 = lane >> 4;
;   bf16x8 cf[4];
;   {
;     const float* cre = p.c_re + ((size_t)(l * 16 + g) * 16 + hcol) * 64;
;     const float* cim = p.c_im + ((size_t)(l * 16 + g) * 16 + hcol) * 64;
; #pragma unroll
;     for (int ks = 0; ks < 4; ++ks) {
;       float v[8];
; #pragma unroll
;       for (int j = 0; j < 8; ++j) {
;         int k = 32 * ks + 8 * q4 + j;
;         v[j] = (k & 1) ? -cim[k >> 1] : cre[k >> 1];
;       }
;       union { bf16x8 v8; u32x4 u; } cv; cv.u = pack8(v); cf[ks] = cv.v8;
;     }
;   }
;   const float dch = p.ssm_d[l * 256 + g * 16 + hcol];
.LBB0_303:
	v_and_b32_e32 v62, 15, v79
	v_lshlrev_b64 v[22:23], 12, v[22:23]
	v_lshrrev_b32_e32 v0, 2, v79
	v_lshl_or_b32 v22, v62, 8, v22
	v_and_b32_e32 v64, 12, v0
	v_lshl_add_u64 v[26:27], s[46:47], 0, v[22:23]
	v_lshlrev_b32_e32 v0, 2, v64
	v_lshl_add_u64 v[58:59], v[26:27], 0, v[0:1]
	global_load_dwordx4 v[70:73], v[58:59], off
	v_lshl_add_u64 v[24:25], s[44:45], 0, v[22:23]
	v_lshl_add_u64 v[54:55], v[24:25], 0, v[0:1]
	global_load_dwordx4 v[74:77], v[54:55], off
	global_load_dwordx4 v[82:85], v[54:55], off offset:64
	global_load_dwordx4 v[86:89], v[58:59], off offset:64
	global_load_dwordx4 v[90:93], v[54:55], off offset:128
	global_load_dwordx4 v[94:97], v[58:59], off offset:128
	global_load_dwordx4 v[98:101], v[54:55], off offset:192
	global_load_dwordx4 v[102:105], v[58:59], off offset:192
	s_movk_i32 s0, 0x1100
	v_mul_lo_u32 v66, v80, s0
	v_add_u32_e32 v56, s33, v66
	v_and_b32_e32 v68, 48, v79
	s_waitcnt vmcnt(10)
	v_mov_b32_e32 v63, v14
	v_mov_b32_e32 v14, v3
	s_mov_b32 s8, 0
	s_waitcnt vmcnt(7)
	v_xor_b32_e32 v0, 0x80000000, v70
	v_xor_b32_e32 v26, 0x80000000, v71
	v_xor_b32_e32 v27, 0x80000000, v72
	v_xor_b32_e32 v28, 0x80000000, v73
	s_waitcnt vmcnt(6)
	v_cvt_pk_bf16_f32 v23, v75, v26
	v_cvt_pk_bf16_f32 v24, v76, v27
	v_cvt_pk_bf16_f32 v25, v77, v28
	v_cvt_pk_bf16_f32 v22, v74, v0
	s_waitcnt vmcnt(4)
	v_xor_b32_e32 v0, 0x80000000, v86
	v_xor_b32_e32 v30, 0x80000000, v87
	v_xor_b32_e32 v31, 0x80000000, v88
	v_xor_b32_e32 v32, 0x80000000, v89
	v_cvt_pk_bf16_f32 v27, v83, v30
	v_cvt_pk_bf16_f32 v28, v84, v31
	v_cvt_pk_bf16_f32 v29, v85, v32
	v_cvt_pk_bf16_f32 v26, v82, v0
	s_waitcnt vmcnt(2)
	v_xor_b32_e32 v0, 0x80000000, v94
	v_xor_b32_e32 v34, 0x80000000, v95
	v_xor_b32_e32 v35, 0x80000000, v96
	v_xor_b32_e32 v36, 0x80000000, v97
	v_cvt_pk_bf16_f32 v31, v91, v34
	v_cvt_pk_bf16_f32 v32, v92, v35
	v_cvt_pk_bf16_f32 v33, v93, v36
	s_nop 0
	s_load_dwordx2 s[0:1], s[10:11], 0xa8
	v_cvt_pk_bf16_f32 v30, v90, v0
	s_waitcnt vmcnt(0)
	v_xor_b32_e32 v0, 0x80000000, v102
	v_lshlrev_b32_e32 v58, 4, v81
	v_xor_b32_e32 v54, 0x80000000, v103
	v_cvt_pk_bf16_f32 v34, v98, v0
	v_add_u32_e32 v0, s56, v58
	v_xor_b32_e32 v55, 0x80000000, v104
	v_cvt_pk_bf16_f32 v35, v99, v54
	v_or_b32_e32 v54, v0, v62
	v_cvt_pk_bf16_f32 v36, v100, v55
	v_ashrrev_i32_e32 v55, 31, v54
	s_waitcnt lgkmcnt(0)
	v_lshl_add_u64 v[54:55], v[54:55], 2, s[0:1]
	global_load_dword v65, v[54:55], off
	v_xor_b32_e32 v57, 0x80000000, v105
	s_movk_i32 s0, 0xef40
	v_mad_u64_u32 v[54:55], s[0:1], v80, s0, v[56:57]
	s_movk_i32 s0, 0x110
	s_nop 0
	v_mad_u32_u24 v67, v62, s0, v56
	s_load_dwordx2 s[0:1], s[10:11], 0x178
	v_ashrrev_i32_e32 v59, 31, v58
	v_cvt_pk_bf16_f32 v37, v101, v57
	v_lshlrev_b32_e32 v0, 1, v62
	v_mov_b32_e32 v60, v46
	s_waitcnt lgkmcnt(0)
	v_lshl_add_u64 v[56:57], v[58:59], 1, s[0:1]
	v_mov_b32_e32 v58, v5
	v_mov_b32_e32 v5, v16
	v_mov_b32_e32 v16, v38
	v_lshl_or_b32 v38, v78, 2, v66
	v_readlane_b32 s0, v254, 24
	v_lshl_add_u64 v[56:57], v[56:57], 0, v[0:1]
	v_lshl_add_u32 v0, v62, 2, v54
	v_mov_b32_e32 v59, v17
	v_mov_b32_e32 v61, v10
	v_mov_b32_e32 v10, v47
	v_mov_b32_e32 v46, v48
	v_mov_b32_e32 v47, v12
	v_mov_b32_e32 v12, v49
	v_mov_b32_e32 v48, v42
	v_mov_b32_e32 v49, v6
	v_mov_b32_e32 v6, v43
	v_mov_b32_e32 v42, v44
	v_mov_b32_e32 v43, v8
	v_mov_b32_e32 v8, v45
	v_mov_b32_e32 v17, v18
	v_mov_b32_e32 v18, v39
	v_mov_b32_e32 v44, v40
	v_mov_b32_e32 v45, v20
	v_mov_b32_e32 v20, v41
	v_mov_b32_e32 v62, v2
	v_pk_mov_b32 v[2:3], v[50:51], v[50:51] op_sel:[1,0]
	v_add_u32_e32 v55, s0, v38
	v_add_u32_e32 v66, v67, v68
	s_waitcnt vmcnt(0)

; DI void kv_tile(PREF p, int l, int idx, unsigned char* ldsb) {
;     ...
;   if (tid < 128) {
;     const u16* src = p.hb + (size_t)(row0 + tid) * HW + OFF_CKV;
;     float ss = 0.f;
;     for (int i = 0; i < 16; ++i) { float f[8]; unpack8(*(const u32x4*)(src + i * 8), f);
; #pragma unroll
;       for (int j = 0; j < 8; ++j) ss += f[j] * f[j]; }
;     aux[tid] = rsqrtf(ss * (1.f / 128.f) + 1e-6f);
.LBB0_338:
	v_mov_b32_e32 v34, v169
	s_and_b32 s24, s23, 0xffffff80
	v_cmp_gt_i32_e32 vcc, s93, v34
	s_waitcnt lgkmcnt(0)
	s_barrier
	s_and_saveexec_b64 s[18:19], vcc
	s_cbranch_execz .LBB0_337
	v_add_u32_e32 v0, s24, v34
	v_mov_b64_e32 v[2:3], s[16:17]
	v_mad_i64_i32 v[14:15], s[0:1], v0, s60, v[2:3]
	global_load_dwordx4 v[24:27], v[14:15], off offset:2096
	global_load_dwordx4 v[28:31], v[14:15], off offset:2080
	global_load_dwordx4 v[36:39], v[14:15], off offset:2064
	global_load_dwordx4 v[40:43], v[14:15], off offset:2048
	global_load_dwordx4 v[44:47], v[14:15], off offset:2160
	global_load_dwordx4 v[48:51], v[14:15], off offset:2144
	global_load_dwordx4 v[52:55], v[14:15], off offset:2128
	global_load_dwordx4 v[56:59], v[14:15], off offset:2112
	global_load_dwordx4 v[60:63], v[14:15], off offset:2224
	global_load_dwordx4 v[64:67], v[14:15], off offset:2208
	global_load_dwordx4 v[68:71], v[14:15], off offset:2192
	global_load_dwordx4 v[72:75], v[14:15], off offset:2176
	global_load_dwordx4 v[76:79], v[14:15], off offset:2288
	global_load_dwordx4 v[80:83], v[14:15], off offset:2272
	global_load_dwordx4 v[84:87], v[14:15], off offset:2256
	global_load_dwordx4 v[88:91], v[14:15], off offset:2240
	v_readlane_b32 s0, v254, 16
	s_waitcnt vmcnt(12)
	v_and_b32_e32 v0, 0xffff0000, v40
	v_lshlrev_b32_e32 v20, 16, v40
	v_mul_f32_e32 v0, v0, v0
	v_lshlrev_b32_e32 v16, 16, v41
	v_fmac_f32_e32 v0, v20, v20
	v_and_b32_e32 v17, 0xffff0000, v41
	v_fmac_f32_e32 v0, v16, v16
	v_lshlrev_b32_e32 v21, 16, v42
	v_fmac_f32_e32 v0, v17, v17
	v_and_b32_e32 v18, 0xffff0000, v42
	v_fmac_f32_e32 v0, v21, v21
	v_lshlrev_b32_e32 v22, 16, v43
	v_fmac_f32_e32 v0, v18, v18
	v_and_b32_e32 v19, 0xffff0000, v43
	v_fmac_f32_e32 v0, v22, v22
	v_fmac_f32_e32 v0, v19, v19
	v_lshlrev_b32_e32 v16, 16, v36
	v_and_b32_e32 v10, 0xffff0000, v36
	v_fmac_f32_e32 v0, v16, v16
	v_lshlrev_b32_e32 v17, 16, v37
	v_fmac_f32_e32 v0, v10, v10
	v_and_b32_e32 v11, 0xffff0000, v37
	v_fmac_f32_e32 v0, v17, v17
	v_lshlrev_b32_e32 v18, 16, v38
	v_fmac_f32_e32 v0, v11, v11
	v_and_b32_e32 v12, 0xffff0000, v38
	v_fmac_f32_e32 v0, v18, v18
	v_lshlrev_b32_e32 v19, 16, v39
	v_fmac_f32_e32 v0, v12, v12
	v_and_b32_e32 v13, 0xffff0000, v39
	v_fmac_f32_e32 v0, v19, v19
	v_fmac_f32_e32 v0, v13, v13
	v_lshlrev_b32_e32 v10, 16, v28
	v_and_b32_e32 v6, 0xffff0000, v28
	v_fmac_f32_e32 v0, v10, v10
	v_lshlrev_b32_e32 v11, 16, v29
	v_fmac_f32_e32 v0, v6, v6
	v_and_b32_e32 v7, 0xffff0000, v29
	v_fmac_f32_e32 v0, v11, v11
	v_lshlrev_b32_e32 v12, 16, v30
	v_fmac_f32_e32 v0, v7, v7
	v_and_b32_e32 v8, 0xffff0000, v30
	v_fmac_f32_e32 v0, v12, v12
	v_lshlrev_b32_e32 v13, 16, v31
	v_fmac_f32_e32 v0, v8, v8
	v_and_b32_e32 v9, 0xffff0000, v31
	v_fmac_f32_e32 v0, v13, v13
	v_fmac_f32_e32 v0, v9, v9
	v_lshlrev_b32_e32 v6, 16, v24
	v_and_b32_e32 v2, 0xffff0000, v24
	v_fmac_f32_e32 v0, v6, v6
	v_lshlrev_b32_e32 v7, 16, v25
	v_fmac_f32_e32 v0, v2, v2
	v_and_b32_e32 v3, 0xffff0000, v25
	v_fmac_f32_e32 v0, v7, v7
	v_lshlrev_b32_e32 v8, 16, v26
	v_fmac_f32_e32 v0, v3, v3
	v_and_b32_e32 v4, 0xffff0000, v26
	v_fmac_f32_e32 v0, v8, v8
	v_lshlrev_b32_e32 v9, 16, v27
	v_fmac_f32_e32 v0, v4, v4
	v_and_b32_e32 v5, 0xffff0000, v27
	v_fmac_f32_e32 v0, v9, v9
	v_fmac_f32_e32 v0, v5, v5
	s_waitcnt vmcnt(8)
	v_lshlrev_b32_e32 v20, 16, v56
	v_and_b32_e32 v16, 0xffff0000, v56
	v_fmac_f32_e32 v0, v20, v20
	v_lshlrev_b32_e32 v21, 16, v57
	v_fmac_f32_e32 v0, v16, v16
	v_and_b32_e32 v17, 0xffff0000, v57
	v_fmac_f32_e32 v0, v21, v21
	v_lshlrev_b32_e32 v22, 16, v58
	v_fmac_f32_e32 v0, v17, v17
	v_and_b32_e32 v18, 0xffff0000, v58
	v_fmac_f32_e32 v0, v22, v22
	v_lshlrev_b32_e32 v23, 16, v59
	v_fmac_f32_e32 v0, v18, v18
	v_and_b32_e32 v19, 0xffff0000, v59
	v_fmac_f32_e32 v0, v23, v23
	v_fmac_f32_e32 v0, v19, v19
	v_lshlrev_b32_e32 v16, 16, v52
	v_and_b32_e32 v10, 0xffff0000, v52
	v_fmac_f32_e32 v0, v16, v16
	v_lshlrev_b32_e32 v17, 16, v53
	v_fmac_f32_e32 v0, v10, v10
	v_and_b32_e32 v11, 0xffff0000, v53
	v_fmac_f32_e32 v0, v17, v17
	v_lshlrev_b32_e32 v18, 16, v54
	v_fmac_f32_e32 v0, v11, v11
	v_and_b32_e32 v12, 0xffff0000, v54
	v_fmac_f32_e32 v0, v18, v18
	v_lshlrev_b32_e32 v19, 16, v55
	v_fmac_f32_e32 v0, v12, v12
	v_and_b32_e32 v13, 0xffff0000, v55
	v_fmac_f32_e32 v0, v19, v19
	v_fmac_f32_e32 v0, v13, v13
	v_lshlrev_b32_e32 v10, 16, v48
	v_and_b32_e32 v6, 0xffff0000, v48
	v_fmac_f32_e32 v0, v10, v10
	v_lshlrev_b32_e32 v11, 16, v49
	v_fmac_f32_e32 v0, v6, v6
	v_and_b32_e32 v7, 0xffff0000, v49
	v_fmac_f32_e32 v0, v11, v11
	v_lshlrev_b32_e32 v12, 16, v50
	v_fmac_f32_e32 v0, v7, v7
	v_and_b32_e32 v8, 0xffff0000, v50
	v_fmac_f32_e32 v0, v12, v12
	v_lshlrev_b32_e32 v13, 16, v51
	v_fmac_f32_e32 v0, v8, v8
	v_and_b32_e32 v9, 0xffff0000, v51
	v_fmac_f32_e32 v0, v13, v13
	v_fmac_f32_e32 v0, v9, v9
	v_lshlrev_b32_e32 v6, 16, v44
	v_and_b32_e32 v2, 0xffff0000, v44
	v_fmac_f32_e32 v0, v6, v6
	v_lshlrev_b32_e32 v7, 16, v45
	v_fmac_f32_e32 v0, v2, v2
	v_and_b32_e32 v3, 0xffff0000, v45
	v_fmac_f32_e32 v0, v7, v7
	v_lshlrev_b32_e32 v8, 16, v46
	v_fmac_f32_e32 v0, v3, v3
	v_and_b32_e32 v4, 0xffff0000, v46
	v_fmac_f32_e32 v0, v8, v8
	v_lshlrev_b32_e32 v9, 16, v47
	v_fmac_f32_e32 v0, v4, v4
	v_and_b32_e32 v5, 0xffff0000, v47
	v_fmac_f32_e32 v0, v9, v9
	v_fmac_f32_e32 v0, v5, v5
	s_waitcnt vmcnt(4)
; DI void kv_tile(PREF p, int l, int idx, unsigned char* ldsb) {
;     ...
;   if (tid < 128) {
;     const u16* src = p.hb + (size_t)(row0 + tid) * HW + OFF_CKV;
;     float ss = 0.f;
;     for (int i = 0; i < 16; ++i) { float f[8]; unpack8(*(const u32x4*)(src + i * 8), f);
; #pragma unroll
;       for (int j = 0; j < 8; ++j) ss += f[j] * f[j]; }
;     aux[tid] = rsqrtf(ss * (1.f / 128.f) + 1e-6f);
	v_lshlrev_b32_e32 v20, 16, v72
	v_and_b32_e32 v16, 0xffff0000, v72
	v_fmac_f32_e32 v0, v20, v20
	v_lshlrev_b32_e32 v21, 16, v73
	v_fmac_f32_e32 v0, v16, v16
	v_and_b32_e32 v17, 0xffff0000, v73
	v_fmac_f32_e32 v0, v21, v21
	v_lshlrev_b32_e32 v22, 16, v74
	v_fmac_f32_e32 v0, v17, v17
	v_and_b32_e32 v18, 0xffff0000, v74
	v_fmac_f32_e32 v0, v22, v22
	v_lshlrev_b32_e32 v23, 16, v75
	v_fmac_f32_e32 v0, v18, v18
	v_and_b32_e32 v19, 0xffff0000, v75
	v_fmac_f32_e32 v0, v23, v23
	v_fmac_f32_e32 v0, v19, v19
	v_lshlrev_b32_e32 v16, 16, v68
	v_and_b32_e32 v10, 0xffff0000, v68
	v_fmac_f32_e32 v0, v16, v16
	v_lshlrev_b32_e32 v17, 16, v69
	v_fmac_f32_e32 v0, v10, v10
	v_and_b32_e32 v11, 0xffff0000, v69
	v_fmac_f32_e32 v0, v17, v17
	v_lshlrev_b32_e32 v18, 16, v70
	v_fmac_f32_e32 v0, v11, v11
	v_and_b32_e32 v12, 0xffff0000, v70
	v_fmac_f32_e32 v0, v18, v18
	v_lshlrev_b32_e32 v19, 16, v71
	v_fmac_f32_e32 v0, v12, v12
	v_and_b32_e32 v13, 0xffff0000, v71
	v_fmac_f32_e32 v0, v19, v19
	v_fmac_f32_e32 v0, v13, v13
	v_lshlrev_b32_e32 v10, 16, v64
	v_and_b32_e32 v6, 0xffff0000, v64
	v_fmac_f32_e32 v0, v10, v10
	v_lshlrev_b32_e32 v11, 16, v65
	v_fmac_f32_e32 v0, v6, v6
	v_and_b32_e32 v7, 0xffff0000, v65
	v_fmac_f32_e32 v0, v11, v11
	v_lshlrev_b32_e32 v12, 16, v66
	v_fmac_f32_e32 v0, v7, v7
	v_and_b32_e32 v8, 0xffff0000, v66
	v_fmac_f32_e32 v0, v12, v12
	v_lshlrev_b32_e32 v13, 16, v67
	v_fmac_f32_e32 v0, v8, v8
	v_and_b32_e32 v9, 0xffff0000, v67
	v_fmac_f32_e32 v0, v13, v13
	v_fmac_f32_e32 v0, v9, v9
	v_lshlrev_b32_e32 v6, 16, v60
	v_and_b32_e32 v2, 0xffff0000, v60
	v_fmac_f32_e32 v0, v6, v6
	v_lshlrev_b32_e32 v7, 16, v61
	v_fmac_f32_e32 v0, v2, v2
	v_and_b32_e32 v3, 0xffff0000, v61
	v_fmac_f32_e32 v0, v7, v7
	v_lshlrev_b32_e32 v8, 16, v62
	v_fmac_f32_e32 v0, v3, v3
	v_and_b32_e32 v4, 0xffff0000, v62
	v_fmac_f32_e32 v0, v8, v8
	v_lshlrev_b32_e32 v9, 16, v63
	v_fmac_f32_e32 v0, v4, v4
	v_and_b32_e32 v5, 0xffff0000, v63
	v_fmac_f32_e32 v0, v9, v9
	v_fmac_f32_e32 v0, v5, v5
	s_nop 0
	s_waitcnt vmcnt(0)
	v_lshlrev_b32_e32 v18, 16, v88
	v_and_b32_e32 v14, 0xffff0000, v88
	v_fmac_f32_e32 v0, v18, v18
	v_lshlrev_b32_e32 v19, 16, v89
	v_fmac_f32_e32 v0, v14, v14
	v_and_b32_e32 v15, 0xffff0000, v89
	v_fmac_f32_e32 v0, v19, v19
	v_lshlrev_b32_e32 v20, 16, v90
	v_fmac_f32_e32 v0, v15, v15
	v_and_b32_e32 v16, 0xffff0000, v90
	v_fmac_f32_e32 v0, v20, v20
	v_lshlrev_b32_e32 v21, 16, v91
	v_fmac_f32_e32 v0, v16, v16
	v_and_b32_e32 v17, 0xffff0000, v91
	v_fmac_f32_e32 v0, v21, v21
	v_fmac_f32_e32 v0, v17, v17
	v_lshlrev_b32_e32 v14, 16, v84
	v_and_b32_e32 v10, 0xffff0000, v84
	v_fmac_f32_e32 v0, v14, v14
	v_lshlrev_b32_e32 v15, 16, v85
	v_fmac_f32_e32 v0, v10, v10
	v_and_b32_e32 v11, 0xffff0000, v85
	v_fmac_f32_e32 v0, v15, v15
	v_lshlrev_b32_e32 v16, 16, v86
	v_fmac_f32_e32 v0, v11, v11
	v_and_b32_e32 v12, 0xffff0000, v86
	v_fmac_f32_e32 v0, v16, v16
	v_lshlrev_b32_e32 v17, 16, v87
	v_fmac_f32_e32 v0, v12, v12
	v_and_b32_e32 v13, 0xffff0000, v87
	v_fmac_f32_e32 v0, v17, v17
	v_fmac_f32_e32 v0, v13, v13
	v_lshlrev_b32_e32 v10, 16, v80
	v_and_b32_e32 v6, 0xffff0000, v80
	v_fmac_f32_e32 v0, v10, v10
	v_lshlrev_b32_e32 v11, 16, v81
	v_fmac_f32_e32 v0, v6, v6
	v_and_b32_e32 v7, 0xffff0000, v81
	v_fmac_f32_e32 v0, v11, v11
	v_lshlrev_b32_e32 v12, 16, v82
	v_fmac_f32_e32 v0, v7, v7
	v_and_b32_e32 v8, 0xffff0000, v82
	v_fmac_f32_e32 v0, v12, v12
	v_and_b32_e32 v6, 0xffff0000, v83
	v_lshlrev_b32_e32 v7, 16, v83
	v_fmac_f32_e32 v0, v8, v8
	v_pk_mul_f32 v[6:7], v[6:7], v[6:7]
	s_nop 0
	v_add_f32_e32 v0, v7, v0
	v_add_f32_e32 v0, v6, v0
	v_and_b32_e32 v6, 0xffff0000, v76
	v_lshlrev_b32_e32 v7, 16, v76
	v_pk_mul_f32 v[6:7], v[6:7], v[6:7]
	v_and_b32_e32 v2, 0xffff0000, v77
	v_add_f32_e32 v0, v7, v0
	v_lshlrev_b32_e32 v3, 16, v77
	v_add_f32_e32 v0, v6, v0
	v_pk_mul_f32 v[2:3], v[2:3], v[2:3]
	s_nop 0
	v_add_f32_e32 v0, v3, v0
	v_add_f32_e32 v0, v2, v0
	v_and_b32_e32 v2, 0xffff0000, v78
	v_lshlrev_b32_e32 v3, 16, v78
	v_pk_mul_f32 v[2:3], v[2:3], v[2:3]
	s_nop 0
	v_add_f32_e32 v0, v3, v0
	v_add_f32_e32 v0, v2, v0
	v_and_b32_e32 v2, 0xffff0000, v79
	v_lshlrev_b32_e32 v3, 16, v79
	v_pk_mul_f32 v[2:3], v[2:3], v[2:3]
	s_nop 0
	v_add_f32_e32 v0, v3, v0
	v_add_f32_e32 v0, v2, v0
	v_fmamk_f32 v0, v0, 0x3c000000, v173
	v_cmp_gt_f32_e32 vcc, s61, v0
	v_mul_f32_e32 v2, 0x4b800000, v0
	s_nop 0
	v_cndmask_b32_e32 v0, v0, v2, vcc
	v_rsq_f32_e32 v0, v0
	s_nop 0
	v_mul_f32_e32 v2, 0x45800000, v0
	v_cndmask_b32_e32 v0, v0, v2, vcc
	v_lshl_add_u32 v2, v34, 2, s0
	ds_write_b32 v2, v0
	s_branch .LBB0_337

; DI void q_tile(PREF p, int l, int idx, unsigned char* ldsb) {
;     ...
;   if (tid < 128) {
;     const u16* src = p.hb + (size_t)(row0 + tid) * HW + OFF_CQ;
;     float ss = 0.f;
;     for (int i = 0; i < 32; ++i) { float f[8]; unpack8(*(const u32x4*)(src + i * 8), f);
; #pragma unroll
;       for (int j = 0; j < 8; ++j) ss += f[j] * f[j]; }
;     aux[tid] = rsqrtf(ss * (1.f / 256.f) + 1e-6f);
.LBB0_344:
	s_mul_hi_i32 s19, s20, 0x55555556
	s_lshr_b32 s0, s19, 31
	v_mov_b32_e32 v82, v169
	s_add_i32 s19, s19, s0
	s_lshl_b32 s18, s19, 7
	v_cmp_gt_i32_e32 vcc, s93, v82
	s_barrier
	s_and_saveexec_b64 s[8:9], vcc
	s_cbranch_execz .LBB0_348
	v_add_u32_e32 v0, s18, v82
	v_mov_b64_e32 v[2:3], s[10:11]
	v_mad_i64_i32 v[2:3], s[0:1], v0, s60, v[2:3]
	v_mov_b32_e32 v0, 0
	s_mov_b64 s[16:17], 0
	global_load_dwordx4 v[24:27], v[2:3], off offset:1584
	global_load_dwordx4 v[28:31], v[2:3], off offset:1568
	global_load_dwordx4 v[32:35], v[2:3], off offset:1552
	global_load_dwordx4 v[36:39], v[2:3], off offset:1536
	global_load_dwordx4 v[40:43], v[2:3], off offset:1648
	global_load_dwordx4 v[44:47], v[2:3], off offset:1632
	global_load_dwordx4 v[48:51], v[2:3], off offset:1616
	global_load_dwordx4 v[52:55], v[2:3], off offset:1600
	global_load_dwordx4 v[56:59], v[2:3], off offset:1712
	global_load_dwordx4 v[60:63], v[2:3], off offset:1696
	global_load_dwordx4 v[64:67], v[2:3], off offset:1680
	global_load_dwordx4 v[68:71], v[2:3], off offset:1664
	global_load_dwordx4 v[72:75], v[2:3], off offset:1776
	global_load_dwordx4 v[76:79], v[2:3], off offset:1760
	global_load_dwordx4 v[84:87], v[2:3], off offset:1744
	global_load_dwordx4 v[88:91], v[2:3], off offset:1728
	global_load_dwordx4 v[92:95], v[2:3], off offset:1840
	global_load_dwordx4 v[96:99], v[2:3], off offset:1824
	global_load_dwordx4 v[100:103], v[2:3], off offset:1808
	global_load_dwordx4 v[104:107], v[2:3], off offset:1792
	global_load_dwordx4 v[108:111], v[2:3], off offset:1904
	global_load_dwordx4 v[112:115], v[2:3], off offset:1888
	global_load_dwordx4 v[116:119], v[2:3], off offset:1872
	global_load_dwordx4 v[120:123], v[2:3], off offset:1856
	global_load_dwordx4 v[124:127], v[2:3], off offset:1968
	global_load_dwordx4 v[128:131], v[2:3], off offset:1952
	global_load_dwordx4 v[132:135], v[2:3], off offset:1936
	global_load_dwordx4 v[136:139], v[2:3], off offset:1920
	global_load_dwordx4 v[140:143], v[2:3], off offset:2032
	global_load_dwordx4 v[144:147], v[2:3], off offset:2016
	global_load_dwordx4 v[148:151], v[2:3], off offset:2000
	global_load_dwordx4 v[152:155], v[2:3], off offset:1984
	s_nop 0
	s_waitcnt vmcnt(28)
	v_lshlrev_b32_e32 v20, 16, v36
	v_fmac_f32_e32 v0, v20, v20
	v_lshlrev_b32_e32 v21, 16, v37
	v_and_b32_e32 v20, 0xffff0000, v36
	v_pk_mul_f32 v[20:21], v[20:21], v[20:21]
	v_and_b32_e32 v22, 0xffff0000, v39
	v_add_f32_e32 v0, v20, v0
	v_add_f32_e32 v0, v21, v0
	v_lshlrev_b32_e32 v21, 16, v38
	v_and_b32_e32 v20, 0xffff0000, v37
	v_pk_mul_f32 v[16:17], v[20:21], v[20:21]
	s_nop 0
	v_add_f32_e32 v0, v16, v0
	v_add_f32_e32 v0, v17, v0
	v_lshlrev_b32_e32 v17, 16, v39
	v_and_b32_e32 v16, 0xffff0000, v38
	v_pk_mul_f32 v[16:17], v[16:17], v[16:17]
	v_and_b32_e32 v18, 0xffff0000, v35
	v_add_f32_e32 v0, v16, v0
	v_add_f32_e32 v0, v17, v0
	v_fmac_f32_e32 v0, v22, v22
	v_lshlrev_b32_e32 v16, 16, v32
	v_fmac_f32_e32 v0, v16, v16
	v_lshlrev_b32_e32 v17, 16, v33
	v_and_b32_e32 v16, 0xffff0000, v32
	v_pk_mul_f32 v[16:17], v[16:17], v[16:17]
	s_nop 0
	v_add_f32_e32 v0, v16, v0
	v_add_f32_e32 v0, v17, v0
	v_lshlrev_b32_e32 v17, 16, v34
	v_and_b32_e32 v16, 0xffff0000, v33
	v_pk_mul_f32 v[12:13], v[16:17], v[16:17]
	s_nop 0
	v_add_f32_e32 v0, v12, v0
	v_add_f32_e32 v0, v13, v0
	v_lshlrev_b32_e32 v13, 16, v35
	v_and_b32_e32 v12, 0xffff0000, v34
	v_pk_mul_f32 v[12:13], v[12:13], v[12:13]
	v_and_b32_e32 v14, 0xffff0000, v31
	v_add_f32_e32 v0, v12, v0
	v_add_f32_e32 v0, v13, v0
	v_fmac_f32_e32 v0, v18, v18
	v_lshlrev_b32_e32 v12, 16, v28
	v_fmac_f32_e32 v0, v12, v12
	v_lshlrev_b32_e32 v13, 16, v29
	v_and_b32_e32 v12, 0xffff0000, v28
	v_pk_mul_f32 v[12:13], v[12:13], v[12:13]
	s_nop 0
	v_add_f32_e32 v0, v12, v0
	v_add_f32_e32 v0, v13, v0
	v_lshlrev_b32_e32 v13, 16, v30
	v_and_b32_e32 v12, 0xffff0000, v29
	v_pk_mul_f32 v[8:9], v[12:13], v[12:13]
	s_nop 0
	v_add_f32_e32 v0, v8, v0
	v_add_f32_e32 v0, v9, v0
	v_lshlrev_b32_e32 v9, 16, v31
	v_and_b32_e32 v8, 0xffff0000, v30
	v_pk_mul_f32 v[8:9], v[8:9], v[8:9]
	v_and_b32_e32 v10, 0xffff0000, v27
	v_add_f32_e32 v0, v8, v0
	v_add_f32_e32 v0, v9, v0
	v_fmac_f32_e32 v0, v14, v14
	v_lshlrev_b32_e32 v8, 16, v24
	v_fmac_f32_e32 v0, v8, v8
	v_lshlrev_b32_e32 v9, 16, v25
	v_and_b32_e32 v8, 0xffff0000, v24
	v_pk_mul_f32 v[8:9], v[8:9], v[8:9]
	s_nop 0
	v_add_f32_e32 v0, v8, v0
	v_add_f32_e32 v0, v9, v0
	v_lshlrev_b32_e32 v9, 16, v26
	v_and_b32_e32 v8, 0xffff0000, v25
	v_pk_mul_f32 v[4:5], v[8:9], v[8:9]
	s_nop 0
	v_add_f32_e32 v0, v4, v0
	v_add_f32_e32 v0, v5, v0
	v_lshlrev_b32_e32 v5, 16, v27
	v_and_b32_e32 v4, 0xffff0000, v26
	v_pk_mul_f32 v[4:5], v[4:5], v[4:5]
	s_nop 0
	v_add_f32_e32 v0, v4, v0
	v_add_f32_e32 v0, v5, v0
	v_fmac_f32_e32 v0, v10, v10
	s_nop 0
	s_waitcnt vmcnt(24)
; DI void q_tile(PREF p, int l, int idx, unsigned char* ldsb) {
;     ...
;   if (tid < 128) {
;     const u16* src = p.hb + (size_t)(row0 + tid) * HW + OFF_CQ;
;     float ss = 0.f;
;     for (int i = 0; i < 32; ++i) { float f[8]; unpack8(*(const u32x4*)(src + i * 8), f);
; #pragma unroll
;       for (int j = 0; j < 8; ++j) ss += f[j] * f[j]; }
;     aux[tid] = rsqrtf(ss * (1.f / 256.f) + 1e-6f);
	v_lshlrev_b32_e32 v20, 16, v52
	v_fmac_f32_e32 v0, v20, v20
	v_lshlrev_b32_e32 v21, 16, v53
	v_and_b32_e32 v20, 0xffff0000, v52
	v_pk_mul_f32 v[20:21], v[20:21], v[20:21]
	v_and_b32_e32 v22, 0xffff0000, v55
	v_add_f32_e32 v0, v20, v0
	v_add_f32_e32 v0, v21, v0
	v_lshlrev_b32_e32 v21, 16, v54
	v_and_b32_e32 v20, 0xffff0000, v53
	v_pk_mul_f32 v[16:17], v[20:21], v[20:21]
	s_nop 0
	v_add_f32_e32 v0, v16, v0
	v_add_f32_e32 v0, v17, v0
	v_lshlrev_b32_e32 v17, 16, v55
	v_and_b32_e32 v16, 0xffff0000, v54
	v_pk_mul_f32 v[16:17], v[16:17], v[16:17]
	v_and_b32_e32 v18, 0xffff0000, v51
	v_add_f32_e32 v0, v16, v0
	v_add_f32_e32 v0, v17, v0
	v_fmac_f32_e32 v0, v22, v22
	v_lshlrev_b32_e32 v16, 16, v48
	v_fmac_f32_e32 v0, v16, v16
	v_lshlrev_b32_e32 v17, 16, v49
	v_and_b32_e32 v16, 0xffff0000, v48
	v_pk_mul_f32 v[16:17], v[16:17], v[16:17]
	s_nop 0
	v_add_f32_e32 v0, v16, v0
	v_add_f32_e32 v0, v17, v0
	v_lshlrev_b32_e32 v17, 16, v50
	v_and_b32_e32 v16, 0xffff0000, v49
	v_pk_mul_f32 v[12:13], v[16:17], v[16:17]
	s_nop 0
	v_add_f32_e32 v0, v12, v0
	v_add_f32_e32 v0, v13, v0
	v_lshlrev_b32_e32 v13, 16, v51
	v_and_b32_e32 v12, 0xffff0000, v50
	v_pk_mul_f32 v[12:13], v[12:13], v[12:13]
	v_and_b32_e32 v14, 0xffff0000, v47
	v_add_f32_e32 v0, v12, v0
	v_add_f32_e32 v0, v13, v0
	v_fmac_f32_e32 v0, v18, v18
	v_lshlrev_b32_e32 v12, 16, v44
	v_fmac_f32_e32 v0, v12, v12
	v_lshlrev_b32_e32 v13, 16, v45
	v_and_b32_e32 v12, 0xffff0000, v44
	v_pk_mul_f32 v[12:13], v[12:13], v[12:13]
	s_nop 0
	v_add_f32_e32 v0, v12, v0
	v_add_f32_e32 v0, v13, v0
	v_lshlrev_b32_e32 v13, 16, v46
	v_and_b32_e32 v12, 0xffff0000, v45
	v_pk_mul_f32 v[8:9], v[12:13], v[12:13]
	s_nop 0
	v_add_f32_e32 v0, v8, v0
	v_add_f32_e32 v0, v9, v0
	v_lshlrev_b32_e32 v9, 16, v47
	v_and_b32_e32 v8, 0xffff0000, v46
	v_pk_mul_f32 v[8:9], v[8:9], v[8:9]
	v_and_b32_e32 v10, 0xffff0000, v43
	v_add_f32_e32 v0, v8, v0
	v_add_f32_e32 v0, v9, v0
	v_fmac_f32_e32 v0, v14, v14
	v_lshlrev_b32_e32 v8, 16, v40
	v_fmac_f32_e32 v0, v8, v8
	v_lshlrev_b32_e32 v9, 16, v41
	v_and_b32_e32 v8, 0xffff0000, v40
	v_pk_mul_f32 v[8:9], v[8:9], v[8:9]
	s_nop 0
	v_add_f32_e32 v0, v8, v0
	v_add_f32_e32 v0, v9, v0
	v_lshlrev_b32_e32 v9, 16, v42
	v_and_b32_e32 v8, 0xffff0000, v41
	v_pk_mul_f32 v[4:5], v[8:9], v[8:9]
	s_nop 0
	v_add_f32_e32 v0, v4, v0
	v_add_f32_e32 v0, v5, v0
	v_lshlrev_b32_e32 v5, 16, v43
	v_and_b32_e32 v4, 0xffff0000, v42
	v_pk_mul_f32 v[4:5], v[4:5], v[4:5]
	s_nop 0
	v_add_f32_e32 v0, v4, v0
	v_add_f32_e32 v0, v5, v0
	v_fmac_f32_e32 v0, v10, v10
	s_nop 0
	s_waitcnt vmcnt(20)
	v_lshlrev_b32_e32 v20, 16, v68
	v_fmac_f32_e32 v0, v20, v20
	v_lshlrev_b32_e32 v21, 16, v69
	v_and_b32_e32 v20, 0xffff0000, v68
	v_pk_mul_f32 v[20:21], v[20:21], v[20:21]
	v_and_b32_e32 v22, 0xffff0000, v71
	v_add_f32_e32 v0, v20, v0
	v_add_f32_e32 v0, v21, v0
	v_lshlrev_b32_e32 v21, 16, v70
	v_and_b32_e32 v20, 0xffff0000, v69
	v_pk_mul_f32 v[16:17], v[20:21], v[20:21]
	s_nop 0
	v_add_f32_e32 v0, v16, v0
	v_add_f32_e32 v0, v17, v0
	v_lshlrev_b32_e32 v17, 16, v71
	v_and_b32_e32 v16, 0xffff0000, v70
	v_pk_mul_f32 v[16:17], v[16:17], v[16:17]
	v_and_b32_e32 v18, 0xffff0000, v67
	v_add_f32_e32 v0, v16, v0
	v_add_f32_e32 v0, v17, v0
	v_fmac_f32_e32 v0, v22, v22
	v_lshlrev_b32_e32 v16, 16, v64
	v_fmac_f32_e32 v0, v16, v16
	v_lshlrev_b32_e32 v17, 16, v65
	v_and_b32_e32 v16, 0xffff0000, v64
	v_pk_mul_f32 v[16:17], v[16:17], v[16:17]
	s_nop 0
	v_add_f32_e32 v0, v16, v0
	v_add_f32_e32 v0, v17, v0
	v_lshlrev_b32_e32 v17, 16, v66
	v_and_b32_e32 v16, 0xffff0000, v65
	v_pk_mul_f32 v[12:13], v[16:17], v[16:17]
	s_nop 0
	v_add_f32_e32 v0, v12, v0
	v_add_f32_e32 v0, v13, v0
	v_lshlrev_b32_e32 v13, 16, v67
	v_and_b32_e32 v12, 0xffff0000, v66
	v_pk_mul_f32 v[12:13], v[12:13], v[12:13]
	v_and_b32_e32 v14, 0xffff0000, v63
	v_add_f32_e32 v0, v12, v0
	v_add_f32_e32 v0, v13, v0
	v_fmac_f32_e32 v0, v18, v18
	v_lshlrev_b32_e32 v12, 16, v60
	v_fmac_f32_e32 v0, v12, v12
	v_lshlrev_b32_e32 v13, 16, v61
	v_and_b32_e32 v12, 0xffff0000, v60
	v_pk_mul_f32 v[12:13], v[12:13], v[12:13]
	s_nop 0
	v_add_f32_e32 v0, v12, v0
	v_add_f32_e32 v0, v13, v0
	v_lshlrev_b32_e32 v13, 16, v62
	v_and_b32_e32 v12, 0xffff0000, v61
	v_pk_mul_f32 v[8:9], v[12:13], v[12:13]
	s_nop 0
	v_add_f32_e32 v0, v8, v0
	v_add_f32_e32 v0, v9, v0
	v_lshlrev_b32_e32 v9, 16, v63
	v_and_b32_e32 v8, 0xffff0000, v62
	v_pk_mul_f32 v[8:9], v[8:9], v[8:9]
	v_and_b32_e32 v10, 0xffff0000, v59
	v_add_f32_e32 v0, v8, v0
	v_add_f32_e32 v0, v9, v0
	v_fmac_f32_e32 v0, v14, v14
	v_lshlrev_b32_e32 v8, 16, v56
	v_fmac_f32_e32 v0, v8, v8
	v_lshlrev_b32_e32 v9, 16, v57
	v_and_b32_e32 v8, 0xffff0000, v56
	v_pk_mul_f32 v[8:9], v[8:9], v[8:9]
	s_nop 0
	v_add_f32_e32 v0, v8, v0
	v_add_f32_e32 v0, v9, v0
	v_lshlrev_b32_e32 v9, 16, v58
	v_and_b32_e32 v8, 0xffff0000, v57
	v_pk_mul_f32 v[4:5], v[8:9], v[8:9]
	s_nop 0
	v_add_f32_e32 v0, v4, v0
	v_add_f32_e32 v0, v5, v0
	v_lshlrev_b32_e32 v5, 16, v59
	v_and_b32_e32 v4, 0xffff0000, v58
	v_pk_mul_f32 v[4:5], v[4:5], v[4:5]
	s_nop 0
	v_add_f32_e32 v0, v4, v0
	v_add_f32_e32 v0, v5, v0
	v_fmac_f32_e32 v0, v10, v10
	s_nop 0
	s_waitcnt vmcnt(16)
; DI void q_tile(PREF p, int l, int idx, unsigned char* ldsb) {
;     ...
;   if (tid < 128) {
;     const u16* src = p.hb + (size_t)(row0 + tid) * HW + OFF_CQ;
;     float ss = 0.f;
;     for (int i = 0; i < 32; ++i) { float f[8]; unpack8(*(const u32x4*)(src + i * 8), f);
; #pragma unroll
;       for (int j = 0; j < 8; ++j) ss += f[j] * f[j]; }
;     aux[tid] = rsqrtf(ss * (1.f / 256.f) + 1e-6f);
	v_lshlrev_b32_e32 v20, 16, v88
	v_fmac_f32_e32 v0, v20, v20
	v_lshlrev_b32_e32 v21, 16, v89
	v_and_b32_e32 v20, 0xffff0000, v88
	v_pk_mul_f32 v[20:21], v[20:21], v[20:21]
	v_and_b32_e32 v22, 0xffff0000, v91
	v_add_f32_e32 v0, v20, v0
	v_add_f32_e32 v0, v21, v0
	v_lshlrev_b32_e32 v21, 16, v90
	v_and_b32_e32 v20, 0xffff0000, v89
	v_pk_mul_f32 v[16:17], v[20:21], v[20:21]
	s_nop 0
	v_add_f32_e32 v0, v16, v0
	v_add_f32_e32 v0, v17, v0
	v_lshlrev_b32_e32 v17, 16, v91
	v_and_b32_e32 v16, 0xffff0000, v90
	v_pk_mul_f32 v[16:17], v[16:17], v[16:17]
	v_and_b32_e32 v18, 0xffff0000, v87
	v_add_f32_e32 v0, v16, v0
	v_add_f32_e32 v0, v17, v0
	v_fmac_f32_e32 v0, v22, v22
	v_lshlrev_b32_e32 v16, 16, v84
	v_fmac_f32_e32 v0, v16, v16
	v_lshlrev_b32_e32 v17, 16, v85
	v_and_b32_e32 v16, 0xffff0000, v84
	v_pk_mul_f32 v[16:17], v[16:17], v[16:17]
	s_nop 0
	v_add_f32_e32 v0, v16, v0
	v_add_f32_e32 v0, v17, v0
	v_lshlrev_b32_e32 v17, 16, v86
	v_and_b32_e32 v16, 0xffff0000, v85
	v_pk_mul_f32 v[12:13], v[16:17], v[16:17]
	s_nop 0
	v_add_f32_e32 v0, v12, v0
	v_add_f32_e32 v0, v13, v0
	v_lshlrev_b32_e32 v13, 16, v87
	v_and_b32_e32 v12, 0xffff0000, v86
	v_pk_mul_f32 v[12:13], v[12:13], v[12:13]
	v_and_b32_e32 v14, 0xffff0000, v79
	v_add_f32_e32 v0, v12, v0
	v_add_f32_e32 v0, v13, v0
	v_fmac_f32_e32 v0, v18, v18
	v_lshlrev_b32_e32 v12, 16, v76
	v_fmac_f32_e32 v0, v12, v12
	v_lshlrev_b32_e32 v13, 16, v77
	v_and_b32_e32 v12, 0xffff0000, v76
	v_pk_mul_f32 v[12:13], v[12:13], v[12:13]
	s_nop 0
	v_add_f32_e32 v0, v12, v0
	v_add_f32_e32 v0, v13, v0
	v_lshlrev_b32_e32 v13, 16, v78
	v_and_b32_e32 v12, 0xffff0000, v77
	v_pk_mul_f32 v[8:9], v[12:13], v[12:13]
	s_nop 0
	v_add_f32_e32 v0, v8, v0
	v_add_f32_e32 v0, v9, v0
	v_lshlrev_b32_e32 v9, 16, v79
	v_and_b32_e32 v8, 0xffff0000, v78
	v_pk_mul_f32 v[8:9], v[8:9], v[8:9]
	v_and_b32_e32 v10, 0xffff0000, v75
	v_add_f32_e32 v0, v8, v0
	v_add_f32_e32 v0, v9, v0
	v_fmac_f32_e32 v0, v14, v14
	v_lshlrev_b32_e32 v8, 16, v72
	v_fmac_f32_e32 v0, v8, v8
	v_lshlrev_b32_e32 v9, 16, v73
	v_and_b32_e32 v8, 0xffff0000, v72
	v_pk_mul_f32 v[8:9], v[8:9], v[8:9]
	s_nop 0
	v_add_f32_e32 v0, v8, v0
	v_add_f32_e32 v0, v9, v0
	v_lshlrev_b32_e32 v9, 16, v74
	v_and_b32_e32 v8, 0xffff0000, v73
	v_pk_mul_f32 v[4:5], v[8:9], v[8:9]
	s_nop 0
	v_add_f32_e32 v0, v4, v0
	v_add_f32_e32 v0, v5, v0
	v_lshlrev_b32_e32 v5, 16, v75
	v_and_b32_e32 v4, 0xffff0000, v74
	v_pk_mul_f32 v[4:5], v[4:5], v[4:5]
	s_nop 0
	v_add_f32_e32 v0, v4, v0
	v_add_f32_e32 v0, v5, v0
	v_fmac_f32_e32 v0, v10, v10
	s_nop 0
	s_waitcnt vmcnt(12)
	v_lshlrev_b32_e32 v20, 16, v104
	v_fmac_f32_e32 v0, v20, v20
	v_lshlrev_b32_e32 v21, 16, v105
	v_and_b32_e32 v20, 0xffff0000, v104
	v_pk_mul_f32 v[20:21], v[20:21], v[20:21]
	v_and_b32_e32 v22, 0xffff0000, v107
	v_add_f32_e32 v0, v20, v0
	v_add_f32_e32 v0, v21, v0
	v_lshlrev_b32_e32 v21, 16, v106
	v_and_b32_e32 v20, 0xffff0000, v105
	v_pk_mul_f32 v[16:17], v[20:21], v[20:21]
	s_nop 0
	v_add_f32_e32 v0, v16, v0
	v_add_f32_e32 v0, v17, v0
	v_lshlrev_b32_e32 v17, 16, v107
	v_and_b32_e32 v16, 0xffff0000, v106
	v_pk_mul_f32 v[16:17], v[16:17], v[16:17]
	v_and_b32_e32 v18, 0xffff0000, v103
	v_add_f32_e32 v0, v16, v0
	v_add_f32_e32 v0, v17, v0
	v_fmac_f32_e32 v0, v22, v22
	v_lshlrev_b32_e32 v16, 16, v100
	v_fmac_f32_e32 v0, v16, v16
	v_lshlrev_b32_e32 v17, 16, v101
	v_and_b32_e32 v16, 0xffff0000, v100
	v_pk_mul_f32 v[16:17], v[16:17], v[16:17]
	s_nop 0
	v_add_f32_e32 v0, v16, v0
	v_add_f32_e32 v0, v17, v0
	v_lshlrev_b32_e32 v17, 16, v102
	v_and_b32_e32 v16, 0xffff0000, v101
	v_pk_mul_f32 v[12:13], v[16:17], v[16:17]
	s_nop 0
	v_add_f32_e32 v0, v12, v0
	v_add_f32_e32 v0, v13, v0
	v_lshlrev_b32_e32 v13, 16, v103
	v_and_b32_e32 v12, 0xffff0000, v102
	v_pk_mul_f32 v[12:13], v[12:13], v[12:13]
	v_and_b32_e32 v14, 0xffff0000, v99
	v_add_f32_e32 v0, v12, v0
	v_add_f32_e32 v0, v13, v0
	v_fmac_f32_e32 v0, v18, v18
	v_lshlrev_b32_e32 v12, 16, v96
	v_fmac_f32_e32 v0, v12, v12
	v_lshlrev_b32_e32 v13, 16, v97
	v_and_b32_e32 v12, 0xffff0000, v96
	v_pk_mul_f32 v[12:13], v[12:13], v[12:13]
	s_nop 0
	v_add_f32_e32 v0, v12, v0
	v_add_f32_e32 v0, v13, v0
	v_lshlrev_b32_e32 v13, 16, v98
	v_and_b32_e32 v12, 0xffff0000, v97
	v_pk_mul_f32 v[8:9], v[12:13], v[12:13]
	s_nop 0
	v_add_f32_e32 v0, v8, v0
	v_add_f32_e32 v0, v9, v0
	v_lshlrev_b32_e32 v9, 16, v99
	v_and_b32_e32 v8, 0xffff0000, v98
	v_pk_mul_f32 v[8:9], v[8:9], v[8:9]
	v_and_b32_e32 v10, 0xffff0000, v95
	v_add_f32_e32 v0, v8, v0
	v_add_f32_e32 v0, v9, v0
	v_fmac_f32_e32 v0, v14, v14
	v_lshlrev_b32_e32 v8, 16, v92
	v_fmac_f32_e32 v0, v8, v8
	v_lshlrev_b32_e32 v9, 16, v93
	v_and_b32_e32 v8, 0xffff0000, v92
	v_pk_mul_f32 v[8:9], v[8:9], v[8:9]
	s_nop 0
	v_add_f32_e32 v0, v8, v0
	v_add_f32_e32 v0, v9, v0
	v_lshlrev_b32_e32 v9, 16, v94
	v_and_b32_e32 v8, 0xffff0000, v93
	v_pk_mul_f32 v[4:5], v[8:9], v[8:9]
	s_nop 0
	v_add_f32_e32 v0, v4, v0
	v_add_f32_e32 v0, v5, v0
	v_lshlrev_b32_e32 v5, 16, v95
	v_and_b32_e32 v4, 0xffff0000, v94
	v_pk_mul_f32 v[4:5], v[4:5], v[4:5]
	s_nop 0
	v_add_f32_e32 v0, v4, v0
	v_add_f32_e32 v0, v5, v0
	v_fmac_f32_e32 v0, v10, v10
	s_nop 0
	s_waitcnt vmcnt(8)
; DI void q_tile(PREF p, int l, int idx, unsigned char* ldsb) {
;     ...
;   if (tid < 128) {
;     const u16* src = p.hb + (size_t)(row0 + tid) * HW + OFF_CQ;
;     float ss = 0.f;
;     for (int i = 0; i < 32; ++i) { float f[8]; unpack8(*(const u32x4*)(src + i * 8), f);
; #pragma unroll
;       for (int j = 0; j < 8; ++j) ss += f[j] * f[j]; }
;     aux[tid] = rsqrtf(ss * (1.f / 256.f) + 1e-6f);
	v_lshlrev_b32_e32 v20, 16, v120
	v_fmac_f32_e32 v0, v20, v20
	v_lshlrev_b32_e32 v21, 16, v121
	v_and_b32_e32 v20, 0xffff0000, v120
	v_pk_mul_f32 v[20:21], v[20:21], v[20:21]
	v_and_b32_e32 v22, 0xffff0000, v123
	v_add_f32_e32 v0, v20, v0
	v_add_f32_e32 v0, v21, v0
	v_lshlrev_b32_e32 v21, 16, v122
	v_and_b32_e32 v20, 0xffff0000, v121
	v_pk_mul_f32 v[16:17], v[20:21], v[20:21]
	s_nop 0
	v_add_f32_e32 v0, v16, v0
	v_add_f32_e32 v0, v17, v0
	v_lshlrev_b32_e32 v17, 16, v123
	v_and_b32_e32 v16, 0xffff0000, v122
	v_pk_mul_f32 v[16:17], v[16:17], v[16:17]
	v_and_b32_e32 v18, 0xffff0000, v119
	v_add_f32_e32 v0, v16, v0
	v_add_f32_e32 v0, v17, v0
	v_fmac_f32_e32 v0, v22, v22
	v_lshlrev_b32_e32 v16, 16, v116
	v_fmac_f32_e32 v0, v16, v16
	v_lshlrev_b32_e32 v17, 16, v117
	v_and_b32_e32 v16, 0xffff0000, v116
	v_pk_mul_f32 v[16:17], v[16:17], v[16:17]
	s_nop 0
	v_add_f32_e32 v0, v16, v0
	v_add_f32_e32 v0, v17, v0
	v_lshlrev_b32_e32 v17, 16, v118
	v_and_b32_e32 v16, 0xffff0000, v117
	v_pk_mul_f32 v[12:13], v[16:17], v[16:17]
	s_nop 0
	v_add_f32_e32 v0, v12, v0
	v_add_f32_e32 v0, v13, v0
	v_lshlrev_b32_e32 v13, 16, v119
	v_and_b32_e32 v12, 0xffff0000, v118
	v_pk_mul_f32 v[12:13], v[12:13], v[12:13]
	v_and_b32_e32 v14, 0xffff0000, v115
	v_add_f32_e32 v0, v12, v0
	v_add_f32_e32 v0, v13, v0
	v_fmac_f32_e32 v0, v18, v18
	v_lshlrev_b32_e32 v12, 16, v112
	v_fmac_f32_e32 v0, v12, v12
	v_lshlrev_b32_e32 v13, 16, v113
	v_and_b32_e32 v12, 0xffff0000, v112
	v_pk_mul_f32 v[12:13], v[12:13], v[12:13]
	s_nop 0
	v_add_f32_e32 v0, v12, v0
	v_add_f32_e32 v0, v13, v0
	v_lshlrev_b32_e32 v13, 16, v114
	v_and_b32_e32 v12, 0xffff0000, v113
	v_pk_mul_f32 v[8:9], v[12:13], v[12:13]
	s_nop 0
	v_add_f32_e32 v0, v8, v0
	v_add_f32_e32 v0, v9, v0
	v_lshlrev_b32_e32 v9, 16, v115
	v_and_b32_e32 v8, 0xffff0000, v114
	v_pk_mul_f32 v[8:9], v[8:9], v[8:9]
	v_and_b32_e32 v10, 0xffff0000, v111
	v_add_f32_e32 v0, v8, v0
	v_add_f32_e32 v0, v9, v0
	v_fmac_f32_e32 v0, v14, v14
	v_lshlrev_b32_e32 v8, 16, v108
	v_fmac_f32_e32 v0, v8, v8
	v_lshlrev_b32_e32 v9, 16, v109
	v_and_b32_e32 v8, 0xffff0000, v108
	v_pk_mul_f32 v[8:9], v[8:9], v[8:9]
	s_nop 0
	v_add_f32_e32 v0, v8, v0
	v_add_f32_e32 v0, v9, v0
	v_lshlrev_b32_e32 v9, 16, v110
	v_and_b32_e32 v8, 0xffff0000, v109
	v_pk_mul_f32 v[4:5], v[8:9], v[8:9]
	s_nop 0
	v_add_f32_e32 v0, v4, v0
	v_add_f32_e32 v0, v5, v0
	v_lshlrev_b32_e32 v5, 16, v111
	v_and_b32_e32 v4, 0xffff0000, v110
	v_pk_mul_f32 v[4:5], v[4:5], v[4:5]
	s_nop 0
	v_add_f32_e32 v0, v4, v0
	v_add_f32_e32 v0, v5, v0
	v_fmac_f32_e32 v0, v10, v10
	s_nop 0
	s_waitcnt vmcnt(4)
	v_lshlrev_b32_e32 v20, 16, v136
	v_fmac_f32_e32 v0, v20, v20
	v_lshlrev_b32_e32 v21, 16, v137
	v_and_b32_e32 v20, 0xffff0000, v136
	v_pk_mul_f32 v[20:21], v[20:21], v[20:21]
	v_and_b32_e32 v22, 0xffff0000, v139
	v_add_f32_e32 v0, v20, v0
	v_add_f32_e32 v0, v21, v0
	v_lshlrev_b32_e32 v21, 16, v138
	v_and_b32_e32 v20, 0xffff0000, v137
	v_pk_mul_f32 v[16:17], v[20:21], v[20:21]
	s_nop 0
	v_add_f32_e32 v0, v16, v0
	v_add_f32_e32 v0, v17, v0
	v_lshlrev_b32_e32 v17, 16, v139
	v_and_b32_e32 v16, 0xffff0000, v138
	v_pk_mul_f32 v[16:17], v[16:17], v[16:17]
	v_and_b32_e32 v18, 0xffff0000, v135
	v_add_f32_e32 v0, v16, v0
	v_add_f32_e32 v0, v17, v0
	v_fmac_f32_e32 v0, v22, v22
	v_lshlrev_b32_e32 v16, 16, v132
	v_fmac_f32_e32 v0, v16, v16
	v_lshlrev_b32_e32 v17, 16, v133
	v_and_b32_e32 v16, 0xffff0000, v132
	v_pk_mul_f32 v[16:17], v[16:17], v[16:17]
	s_nop 0
	v_add_f32_e32 v0, v16, v0
	v_add_f32_e32 v0, v17, v0
	v_lshlrev_b32_e32 v17, 16, v134
	v_and_b32_e32 v16, 0xffff0000, v133
	v_pk_mul_f32 v[12:13], v[16:17], v[16:17]
	s_nop 0
	v_add_f32_e32 v0, v12, v0
	v_add_f32_e32 v0, v13, v0
	v_lshlrev_b32_e32 v13, 16, v135
	v_and_b32_e32 v12, 0xffff0000, v134
	v_pk_mul_f32 v[12:13], v[12:13], v[12:13]
	v_and_b32_e32 v14, 0xffff0000, v131
	v_add_f32_e32 v0, v12, v0
	v_add_f32_e32 v0, v13, v0
	v_fmac_f32_e32 v0, v18, v18
	v_lshlrev_b32_e32 v12, 16, v128
	v_fmac_f32_e32 v0, v12, v12
	v_lshlrev_b32_e32 v13, 16, v129
	v_and_b32_e32 v12, 0xffff0000, v128
	v_pk_mul_f32 v[12:13], v[12:13], v[12:13]
	s_nop 0
	v_add_f32_e32 v0, v12, v0
	v_add_f32_e32 v0, v13, v0
	v_lshlrev_b32_e32 v13, 16, v130
	v_and_b32_e32 v12, 0xffff0000, v129
	v_pk_mul_f32 v[8:9], v[12:13], v[12:13]
	s_nop 0
	v_add_f32_e32 v0, v8, v0
	v_add_f32_e32 v0, v9, v0
	v_lshlrev_b32_e32 v9, 16, v131
	v_and_b32_e32 v8, 0xffff0000, v130
	v_pk_mul_f32 v[8:9], v[8:9], v[8:9]
	v_and_b32_e32 v10, 0xffff0000, v127
	v_add_f32_e32 v0, v8, v0
	v_add_f32_e32 v0, v9, v0
	v_fmac_f32_e32 v0, v14, v14
	v_lshlrev_b32_e32 v8, 16, v124
	v_fmac_f32_e32 v0, v8, v8
	v_lshlrev_b32_e32 v9, 16, v125
	v_and_b32_e32 v8, 0xffff0000, v124
	v_pk_mul_f32 v[8:9], v[8:9], v[8:9]
	s_nop 0
	v_add_f32_e32 v0, v8, v0
	v_add_f32_e32 v0, v9, v0
	v_lshlrev_b32_e32 v9, 16, v126
	v_and_b32_e32 v8, 0xffff0000, v125
	v_pk_mul_f32 v[4:5], v[8:9], v[8:9]
	s_nop 0
	v_add_f32_e32 v0, v4, v0
	v_add_f32_e32 v0, v5, v0
	v_lshlrev_b32_e32 v5, 16, v127
	v_and_b32_e32 v4, 0xffff0000, v126
	v_pk_mul_f32 v[4:5], v[4:5], v[4:5]
	s_nop 0
	v_add_f32_e32 v0, v4, v0
	v_add_f32_e32 v0, v5, v0
	v_fmac_f32_e32 v0, v10, v10
	s_nop 0
	s_waitcnt vmcnt(0)
; DI void q_tile(PREF p, int l, int idx, unsigned char* ldsb) {
;     ...
;   if (tid < 128) {
;     const u16* src = p.hb + (size_t)(row0 + tid) * HW + OFF_CQ;
;     float ss = 0.f;
;     for (int i = 0; i < 32; ++i) { float f[8]; unpack8(*(const u32x4*)(src + i * 8), f);
; #pragma unroll
;       for (int j = 0; j < 8; ++j) ss += f[j] * f[j]; }
;     aux[tid] = rsqrtf(ss * (1.f / 256.f) + 1e-6f);
	v_lshlrev_b32_e32 v20, 16, v152
	v_fmac_f32_e32 v0, v20, v20
	v_lshlrev_b32_e32 v21, 16, v153
	v_and_b32_e32 v20, 0xffff0000, v152
	v_pk_mul_f32 v[20:21], v[20:21], v[20:21]
	v_and_b32_e32 v22, 0xffff0000, v155
	v_add_f32_e32 v0, v20, v0
	v_add_f32_e32 v0, v21, v0
	v_lshlrev_b32_e32 v21, 16, v154
	v_and_b32_e32 v20, 0xffff0000, v153
	v_pk_mul_f32 v[16:17], v[20:21], v[20:21]
	s_nop 0
	v_add_f32_e32 v0, v16, v0
	v_add_f32_e32 v0, v17, v0
	v_lshlrev_b32_e32 v17, 16, v155
	v_and_b32_e32 v16, 0xffff0000, v154
	v_pk_mul_f32 v[16:17], v[16:17], v[16:17]
	v_and_b32_e32 v18, 0xffff0000, v151
	v_add_f32_e32 v0, v16, v0
	v_add_f32_e32 v0, v17, v0
	v_fmac_f32_e32 v0, v22, v22
	v_lshlrev_b32_e32 v16, 16, v148
	v_fmac_f32_e32 v0, v16, v16
	v_lshlrev_b32_e32 v17, 16, v149
	v_and_b32_e32 v16, 0xffff0000, v148
	v_pk_mul_f32 v[16:17], v[16:17], v[16:17]
	s_nop 0
	v_add_f32_e32 v0, v16, v0
	v_add_f32_e32 v0, v17, v0
	v_lshlrev_b32_e32 v17, 16, v150
	v_and_b32_e32 v16, 0xffff0000, v149
	v_pk_mul_f32 v[12:13], v[16:17], v[16:17]
	s_nop 0
	v_add_f32_e32 v0, v12, v0
	v_add_f32_e32 v0, v13, v0
	v_lshlrev_b32_e32 v13, 16, v151
	v_and_b32_e32 v12, 0xffff0000, v150
	v_pk_mul_f32 v[12:13], v[12:13], v[12:13]
	v_and_b32_e32 v14, 0xffff0000, v147
	v_add_f32_e32 v0, v12, v0
	v_add_f32_e32 v0, v13, v0
	v_fmac_f32_e32 v0, v18, v18
	v_lshlrev_b32_e32 v12, 16, v144
	v_fmac_f32_e32 v0, v12, v12
	v_lshlrev_b32_e32 v13, 16, v145
	v_and_b32_e32 v12, 0xffff0000, v144
	v_pk_mul_f32 v[12:13], v[12:13], v[12:13]
	s_nop 0
	v_add_f32_e32 v0, v12, v0
	v_add_f32_e32 v0, v13, v0
	v_lshlrev_b32_e32 v13, 16, v146
	v_and_b32_e32 v12, 0xffff0000, v145
	v_pk_mul_f32 v[8:9], v[12:13], v[12:13]
	s_nop 0
	v_add_f32_e32 v0, v8, v0
	v_add_f32_e32 v0, v9, v0
	v_lshlrev_b32_e32 v9, 16, v147
	v_and_b32_e32 v8, 0xffff0000, v146
	v_pk_mul_f32 v[8:9], v[8:9], v[8:9]
	v_and_b32_e32 v10, 0xffff0000, v143
	v_add_f32_e32 v0, v8, v0
	v_add_f32_e32 v0, v9, v0
	v_fmac_f32_e32 v0, v14, v14
	v_lshlrev_b32_e32 v8, 16, v140
	v_fmac_f32_e32 v0, v8, v8
	v_lshlrev_b32_e32 v9, 16, v141
	v_and_b32_e32 v8, 0xffff0000, v140
	v_pk_mul_f32 v[8:9], v[8:9], v[8:9]
	s_nop 0
	v_add_f32_e32 v0, v8, v0
	v_add_f32_e32 v0, v9, v0
	v_lshlrev_b32_e32 v9, 16, v142
	v_and_b32_e32 v8, 0xffff0000, v141
	v_pk_mul_f32 v[4:5], v[8:9], v[8:9]
	s_nop 0
	v_add_f32_e32 v0, v4, v0
	v_add_f32_e32 v0, v5, v0
	v_lshlrev_b32_e32 v5, 16, v143
	v_and_b32_e32 v4, 0xffff0000, v142
	v_pk_mul_f32 v[4:5], v[4:5], v[4:5]
	s_nop 0
	v_add_f32_e32 v0, v4, v0
	v_add_f32_e32 v0, v5, v0
	v_fmac_f32_e32 v0, v10, v10
	v_fmamk_f32 v0, v0, 0x3b800000, v173
	v_mul_f32_e32 v2, 0x4b800000, v0
	v_cmp_gt_f32_e32 vcc, s61, v0
	v_readlane_b32 s0, v254, 16
	s_nop 0
	v_cndmask_b32_e32 v0, v0, v2, vcc
	v_rsq_f32_e32 v0, v0
	s_nop 0
	v_mul_f32_e32 v2, 0x45800000, v0
	v_cndmask_b32_e32 v0, v0, v2, vcc
	v_lshl_add_u32 v2, v82, 2, s0
	ds_write_b32 v2, v0
